# accumulator zeroing via v_mov_b64 pairs (63 fewer VALU per tile per wave) on top of best
# speedup vs baseline: 1.0031x; 1.0030x over previous
; template <class Epi, class Sched, bool ALIGN_EPI = false, bool SP2 = false>
; __device__ __forceinline__ void gemm_phase(PG8_LAS unsigned char* lds, const Gemm g, const Sched& S, const Epi& E) {
;     ...
; #pragma unroll
;     for (int a = 0; a < 2; ++a)
; #pragma unroll
;         for (int b = 0; b < 2; ++b)
; #pragma unroll
;             for (int m = 0; m < 4; ++m)
; #pragma unroll
;                 for (int n = 0; n < 2; ++n) acc[a][b][m][n] = (f32x4){0.f, 0.f, 0.f, 0.f};
;     ...
; #pragma unroll
;         for (int a = 0; a < 2; ++a)
; #pragma unroll
;             for (int b = 0; b < 2; ++b)
; #pragma unroll
;                 for (int m = 0; m < 4; ++m)
; #pragma unroll
;                     for (int n = 0; n < 2; ++n) acc[a][b][m][n] = (f32x4){0.f, 0.f, 0.f, 0.f};
;         cur = nxt; cA = nA; cB = nB; ++ui;
.LBB0_364:
	s_ashr_i32 s21, s20, 31
	s_lshl_b64 s[10:11], s[20:21], 21
	s_add_u32 s22, s54, s10
	s_addc_u32 s23, s55, s11
	s_and_b64 s[10:11], s[6:7], exec
	s_cselect_b32 s9, s23, s61
	s_cselect_b32 s10, s22, s60
	s_ashr_i32 s19, s18, 31
	s_lshl_b64 s[24:25], s[18:19], 21
	s_add_u32 s56, s88, s24
	s_addc_u32 s57, s89, s25
	s_and_b64 s[24:25], s[6:7], exec
	s_cselect_b32 s11, s57, s67
	s_cselect_b32 s19, s56, s66
	s_add_u32 s60, s60, 0x100080
	s_addc_u32 s61, s61, 0
	s_add_u32 s21, s66, 0x100
	v_mov_b32_e32 v2, 0
	s_addc_u32 s72, s67, 0
	s_mov_b32 s73, -2
	v_mov_b32_e32 v3, v2
	v_mov_b64_e32 v[4:5], 0
	v_mov_b64_e32 v[6:7], 0
	v_mov_b64_e32 v[8:9], 0
	s_waitcnt vmcnt(0)
	v_mov_b64_e32 v[18:19], 0
	v_mov_b64_e32 v[20:21], 0
	v_mov_b64_e32 v[22:23], 0
	v_mov_b64_e32 v[24:25], 0
	v_mov_b64_e32 v[34:35], 0
	v_mov_b64_e32 v[36:37], 0
	v_mov_b64_e32 v[38:39], 0
	v_mov_b64_e32 v[40:41], 0
	v_mov_b64_e32 v[50:51], 0
	v_mov_b64_e32 v[52:53], 0
	v_mov_b64_e32 v[54:55], 0
	v_mov_b64_e32 v[56:57], 0
	v_mov_b64_e32 v[10:11], 0
	v_mov_b64_e32 v[12:13], 0
	v_mov_b64_e32 v[14:15], 0
	v_mov_b64_e32 v[16:17], 0
	v_mov_b64_e32 v[26:27], 0
	v_mov_b64_e32 v[28:29], 0
	v_mov_b64_e32 v[30:31], 0
	v_mov_b64_e32 v[32:33], 0
	v_mov_b64_e32 v[42:43], 0
	v_mov_b64_e32 v[44:45], 0
	v_mov_b64_e32 v[46:47], 0
	v_mov_b64_e32 v[48:49], 0
	v_mov_b64_e32 v[58:59], 0
	v_mov_b64_e32 v[60:61], 0
	v_mov_b64_e32 v[62:63], 0
	v_mov_b64_e32 v[64:65], 0
	v_mov_b64_e32 v[66:67], 0
	v_mov_b64_e32 v[68:69], 0
	v_mov_b64_e32 v[70:71], 0
	v_mov_b64_e32 v[72:73], 0
	v_mov_b64_e32 v[82:83], 0
	v_mov_b64_e32 v[84:85], 0
	v_mov_b64_e32 v[86:87], 0
	v_mov_b64_e32 v[88:89], 0
	v_mov_b64_e32 v[98:99], 0
	v_mov_b64_e32 v[100:101], 0
	v_mov_b64_e32 v[102:103], 0
	v_mov_b64_e32 v[104:105], 0
	v_mov_b64_e32 v[114:115], 0
	v_mov_b64_e32 v[116:117], 0
	v_mov_b64_e32 v[118:119], 0
	v_mov_b64_e32 v[120:121], 0
	v_mov_b64_e32 v[74:75], 0
	v_mov_b64_e32 v[76:77], 0
	v_mov_b64_e32 v[78:79], 0
	v_mov_b64_e32 v[80:81], 0
	v_mov_b64_e32 v[90:91], 0
	v_mov_b64_e32 v[92:93], 0
	v_mov_b64_e32 v[94:95], 0
	v_mov_b64_e32 v[96:97], 0
	v_mov_b64_e32 v[106:107], 0
	v_mov_b64_e32 v[108:109], 0
	v_mov_b64_e32 v[110:111], 0
	v_mov_b64_e32 v[112:113], 0
	v_mov_b64_e32 v[122:123], 0
	v_mov_b64_e32 v[124:125], 0
	v_mov_b64_e32 v[126:127], 0
	v_mov_b64_e32 v[128:129], 0
	s_setprio 1
	s_cmp_eq_u64 s[16:17], 0
	s_cbranch_scc1 .Lsp_LBB0_365
	s_setprio 0

; template <class Epi, class Sched, bool ALIGN_EPI = false, bool SP2 = false>
; __device__ __forceinline__ void gemm_phase(PG8_LAS unsigned char* lds, const Gemm g, const Sched& S, const Epi& E) {
;     ...
; #pragma unroll
;     for (int a = 0; a < 2; ++a)
; #pragma unroll
;         for (int b = 0; b < 2; ++b)
; #pragma unroll
;             for (int m = 0; m < 4; ++m)
; #pragma unroll
;                 for (int n = 0; n < 2; ++n) acc[a][b][m][n] = (f32x4){0.f, 0.f, 0.f, 0.f};
;     ...
; #pragma unroll
;         for (int a = 0; a < 2; ++a)
; #pragma unroll
;             for (int b = 0; b < 2; ++b)
; #pragma unroll
;                 for (int m = 0; m < 4; ++m)
; #pragma unroll
;                     for (int n = 0; n < 2; ++n) acc[a][b][m][n] = (f32x4){0.f, 0.f, 0.f, 0.f};
;         cur = nxt; cA = nA; cB = nB; ++ui;
.LBB0_522:
	v_mov_b32_e32 v129, 0
	s_andn2_b64 vcc, exec, s[16:17]
	v_mov_b32_e32 v128, v129
	v_mov_b32_e32 v127, v129
	v_mov_b32_e32 v126, v129
	v_mov_b32_e32 v125, v129
	v_mov_b32_e32 v124, v129
	v_mov_b32_e32 v123, v129
	v_mov_b32_e32 v122, v129
	v_mov_b32_e32 v121, v129
	v_mov_b32_e32 v120, v129
	v_mov_b32_e32 v119, v129
	v_mov_b32_e32 v118, v129
	v_mov_b32_e32 v117, v129
	v_mov_b32_e32 v116, v129
	v_mov_b32_e32 v115, v129
	v_mov_b32_e32 v114, v129
	v_mov_b32_e32 v113, v129
	v_mov_b32_e32 v112, v129
	v_mov_b32_e32 v111, v129
	v_mov_b32_e32 v110, v129
	v_mov_b32_e32 v109, v129
	v_mov_b32_e32 v108, v129
	v_mov_b32_e32 v107, v129
	v_mov_b32_e32 v106, v129
	v_mov_b32_e32 v105, v129
	v_mov_b32_e32 v104, v129
	v_mov_b32_e32 v103, v129
	v_mov_b32_e32 v102, v129
	v_mov_b32_e32 v101, v129
	v_mov_b32_e32 v100, v129
	v_mov_b32_e32 v99, v129
	v_mov_b32_e32 v98, v129
	v_mov_b32_e32 v65, v129
	v_mov_b32_e32 v64, v129
	v_mov_b32_e32 v63, v129
	v_mov_b32_e32 v62, v129
	v_mov_b32_e32 v61, v129
	v_mov_b32_e32 v60, v129
	v_mov_b32_e32 v59, v129
	v_mov_b32_e32 v58, v129
	v_mov_b32_e32 v57, v129
	v_mov_b32_e32 v56, v129
	v_mov_b32_e32 v55, v129
	v_mov_b32_e32 v54, v129
	v_mov_b32_e32 v53, v129
	v_mov_b32_e32 v52, v129
	v_mov_b32_e32 v51, v129
	v_mov_b32_e32 v50, v129
	v_mov_b32_e32 v49, v129
	v_mov_b32_e32 v48, v129
	v_mov_b32_e32 v47, v129
	v_mov_b32_e32 v46, v129
	v_mov_b32_e32 v45, v129
	v_mov_b32_e32 v44, v129
	v_mov_b32_e32 v43, v129
	v_mov_b32_e32 v42, v129
	v_mov_b32_e32 v41, v129
	v_mov_b32_e32 v40, v129
	v_mov_b32_e32 v39, v129
	v_mov_b32_e32 v38, v129
	v_mov_b32_e32 v37, v129
	v_mov_b32_e32 v36, v129
	v_mov_b32_e32 v35, v129
	v_mov_b32_e32 v34, v129
	v_mov_b32_e32 v97, v129
	v_mov_b32_e32 v96, v129
	v_mov_b32_e32 v95, v129
	v_mov_b32_e32 v94, v129
	v_mov_b32_e32 v93, v129
	v_mov_b32_e32 v92, v129
	v_mov_b32_e32 v91, v129
	v_mov_b32_e32 v90, v129
	v_mov_b32_e32 v89, v129
	v_mov_b32_e32 v88, v129
	v_mov_b32_e32 v87, v129
	v_mov_b32_e32 v86, v129
	v_mov_b32_e32 v85, v129
	v_mov_b32_e32 v84, v129
	v_mov_b32_e32 v83, v129
	v_mov_b32_e32 v82, v129
	v_mov_b32_e32 v81, v129
	v_mov_b32_e32 v80, v129
	v_mov_b32_e32 v79, v129
	v_mov_b32_e32 v78, v129
	v_mov_b32_e32 v77, v129
	v_mov_b32_e32 v76, v129
	v_mov_b32_e32 v75, v129
	v_mov_b32_e32 v74, v129
	v_mov_b32_e32 v73, v129
	v_mov_b32_e32 v72, v129
	v_mov_b32_e32 v71, v129
	v_mov_b32_e32 v70, v129
	v_mov_b32_e32 v69, v129
	v_mov_b32_e32 v68, v129
	v_mov_b32_e32 v67, v129
	v_mov_b32_e32 v66, v129
	v_mov_b32_e32 v33, v129
	v_mov_b32_e32 v32, v129
	v_mov_b32_e32 v31, v129
	v_mov_b32_e32 v30, v129
	v_mov_b32_e32 v29, v129
	v_mov_b32_e32 v28, v129
	v_mov_b32_e32 v27, v129
	v_mov_b32_e32 v26, v129
	v_mov_b32_e32 v25, v129
	v_mov_b32_e32 v24, v129
	v_mov_b32_e32 v23, v129
	v_mov_b32_e32 v22, v129
	v_mov_b32_e32 v21, v129
	v_mov_b32_e32 v20, v129
	v_mov_b32_e32 v19, v129
	v_mov_b32_e32 v18, v129
	v_mov_b32_e32 v17, v129
	v_mov_b32_e32 v16, v129
	v_mov_b32_e32 v15, v129
	v_mov_b32_e32 v14, v129
	v_mov_b32_e32 v13, v129
	v_mov_b32_e32 v12, v129
	v_mov_b32_e32 v11, v129
	v_mov_b32_e32 v10, v129
	v_mov_b32_e32 v9, v129
	v_mov_b32_e32 v8, v129
	v_mov_b32_e32 v7, v129
	v_mov_b32_e32 v6, v129
	v_mov_b32_e32 v5, v129
	v_mov_b32_e32 v4, v129
	v_mov_b32_e32 v3, v129
	v_mov_b32_e32 v2, v129
	s_cbranch_vccnz .LBB0_525
	s_add_u32 s73, s68, 0x100
	v_mov_b32_e32 v2, 0
	s_addc_u32 s74, s69, 0
	s_mov_b32 s24, 0
	v_mov_b32_e32 v3, v2
	v_mov_b64_e32 v[4:5], 0
	v_mov_b64_e32 v[6:7], 0
	v_mov_b64_e32 v[8:9], 0
	v_mov_b64_e32 v[10:11], 0
	v_mov_b64_e32 v[12:13], 0
	v_mov_b64_e32 v[14:15], 0
	v_mov_b64_e32 v[16:17], 0
	v_mov_b64_e32 v[18:19], 0
	v_mov_b64_e32 v[20:21], 0
	v_mov_b64_e32 v[22:23], 0
	v_mov_b64_e32 v[24:25], 0
	v_mov_b64_e32 v[26:27], 0
	v_mov_b64_e32 v[28:29], 0
	v_mov_b64_e32 v[30:31], 0
	v_mov_b64_e32 v[32:33], 0
	v_mov_b64_e32 v[66:67], 0
	v_mov_b64_e32 v[68:69], 0
	v_mov_b64_e32 v[70:71], 0
	v_mov_b64_e32 v[72:73], 0
	v_mov_b64_e32 v[74:75], 0
	v_mov_b64_e32 v[76:77], 0
	v_mov_b64_e32 v[78:79], 0
	v_mov_b64_e32 v[80:81], 0
	v_mov_b64_e32 v[82:83], 0
	v_mov_b64_e32 v[84:85], 0
	v_mov_b64_e32 v[86:87], 0
	v_mov_b64_e32 v[88:89], 0
	v_mov_b64_e32 v[90:91], 0
	v_mov_b64_e32 v[92:93], 0
	v_mov_b64_e32 v[94:95], 0
	v_mov_b64_e32 v[96:97], 0
	v_mov_b64_e32 v[34:35], 0
	v_mov_b64_e32 v[36:37], 0
	v_mov_b64_e32 v[38:39], 0
	v_mov_b64_e32 v[40:41], 0
	v_mov_b64_e32 v[42:43], 0
	v_mov_b64_e32 v[44:45], 0
	v_mov_b64_e32 v[46:47], 0
	v_mov_b64_e32 v[48:49], 0
	v_mov_b64_e32 v[50:51], 0
	v_mov_b64_e32 v[52:53], 0
	v_mov_b64_e32 v[54:55], 0
	v_mov_b64_e32 v[56:57], 0
	v_mov_b64_e32 v[58:59], 0
	v_mov_b64_e32 v[60:61], 0
	v_mov_b64_e32 v[62:63], 0
	v_mov_b64_e32 v[64:65], 0
	v_mov_b64_e32 v[98:99], 0
	v_mov_b64_e32 v[100:101], 0
	v_mov_b64_e32 v[102:103], 0
	v_mov_b64_e32 v[104:105], 0
	v_mov_b64_e32 v[106:107], 0
	v_mov_b64_e32 v[108:109], 0
	v_mov_b64_e32 v[110:111], 0
	v_mov_b64_e32 v[112:113], 0
	v_mov_b64_e32 v[114:115], 0
	v_mov_b64_e32 v[116:117], 0
	v_mov_b64_e32 v[118:119], 0
	v_mov_b64_e32 v[120:121], 0
	v_mov_b64_e32 v[122:123], 0
	v_mov_b64_e32 v[124:125], 0
	v_mov_b64_e32 v[126:127], 0
	v_mov_b64_e32 v[128:129], 0

; template <class Epi, class Sched, bool ALIGN_EPI = false, bool SP2 = false>
; __device__ __forceinline__ void gemm_phase(PG8_LAS unsigned char* lds, const Gemm g, const Sched& S, const Epi& E) {
;     ...
;         const char* nA = has_next ? (const char*)g.A + (size_t)nxt.pm * tstepA + (size_t)((nxt.pn >> g.a_shift) * g.a_stride) : cA; const char* nB = has_next ? (const char*)g.Bt + (size_t)nxt.pn * tstepB : cB;
; #pragma clang loop unroll(disable)
;         for (int t = 0; t < nt; t += 2) {
;             const bool last = (t == nt - 2);
;             const char* a1 = cA + (size_t)(t + 1) * kstep;
;             const char* a2 = last ? nA : cA + (size_t)(t + 2) * kstep; const char* b2 = last ? nB : cB + (size_t)(t + 2) * kstep;
;             const char* a3 = a2 + kstep; const char* b3 = b2 + kstep;
;     ...
; #pragma unroll
;         for (int a = 0; a < 2; ++a)
; #pragma unroll
;             for (int b = 0; b < 2; ++b)
; #pragma unroll
;                 for (int m = 0; m < 4; ++m)
; #pragma unroll
;                     for (int n = 0; n < 2; ++n) acc[a][b][m][n] = (f32x4){0.f, 0.f, 0.f, 0.f};
.LBB0_838:
	s_ashr_i32 s17, s16, 31
	s_lshl_b64 s[18:19], s[16:17], 21
	s_add_u32 s18, s31, s18
	s_addc_u32 s19, s58, s19
	s_and_b64 s[20:21], s[4:5], exec
	s_cselect_b32 s17, s19, s37
	s_cselect_b32 s49, s18, s36
	s_ashr_i32 s15, s14, 31
	s_lshl_b64 s[20:21], s[14:15], 21
	v_readlane_b32 s24, v254, 38
	v_readlane_b32 s25, v254, 39
	s_add_u32 s20, s24, s20
	s_addc_u32 s21, s25, s21
	s_and_b64 s[24:25], s[4:5], exec
	s_cselect_b32 s15, s21, s39
	s_cselect_b32 s62, s20, s38
	s_add_u32 s36, s36, 0x100080
	s_addc_u32 s37, s37, 0
	s_add_u32 s63, s38, 0x100
	v_mov_b32_e32 v2, 0
	s_addc_u32 s68, s39, 0
	s_mov_b32 s69, -2
	v_mov_b32_e32 v3, v2
	v_mov_b64_e32 v[4:5], 0
	v_mov_b64_e32 v[6:7], 0
	v_mov_b64_e32 v[8:9], 0
	v_mov_b64_e32 v[14:15], 0
	v_mov_b64_e32 v[16:17], 0
	v_mov_b64_e32 v[22:23], 0
	v_mov_b64_e32 v[24:25], 0
	v_mov_b64_e32 v[30:31], 0
	v_mov_b64_e32 v[32:33], 0
	v_mov_b64_e32 v[38:39], 0
	v_mov_b64_e32 v[40:41], 0
	v_mov_b64_e32 v[46:47], 0
	v_mov_b64_e32 v[48:49], 0
	v_mov_b64_e32 v[54:55], 0
	v_mov_b64_e32 v[56:57], 0
	v_mov_b64_e32 v[10:11], 0
	v_mov_b64_e32 v[12:13], 0
	v_mov_b64_e32 v[18:19], 0
	v_mov_b64_e32 v[20:21], 0
	v_mov_b64_e32 v[26:27], 0
	v_mov_b64_e32 v[28:29], 0
	v_mov_b64_e32 v[34:35], 0
	v_mov_b64_e32 v[36:37], 0
	v_mov_b64_e32 v[42:43], 0
	v_mov_b64_e32 v[44:45], 0
	v_mov_b64_e32 v[50:51], 0
	v_mov_b64_e32 v[52:53], 0
	v_mov_b64_e32 v[58:59], 0
	v_mov_b64_e32 v[60:61], 0
	v_mov_b64_e32 v[62:63], 0
	v_mov_b64_e32 v[64:65], 0
	v_mov_b64_e32 v[66:67], 0
	v_mov_b64_e32 v[68:69], 0
	v_mov_b64_e32 v[70:71], 0
	v_mov_b64_e32 v[72:73], 0
	v_mov_b64_e32 v[74:75], 0
	v_mov_b64_e32 v[76:77], 0
	v_mov_b64_e32 v[78:79], 0
	v_mov_b64_e32 v[80:81], 0
	v_mov_b64_e32 v[82:83], 0
	v_mov_b64_e32 v[84:85], 0
	v_mov_b64_e32 v[90:91], 0
	v_mov_b64_e32 v[92:93], 0
	v_mov_b64_e32 v[98:99], 0
	v_mov_b64_e32 v[100:101], 0
	v_mov_b64_e32 v[106:107], 0
	v_mov_b64_e32 v[108:109], 0
	v_mov_b64_e32 v[86:87], 0
	v_mov_b64_e32 v[88:89], 0
	v_mov_b64_e32 v[94:95], 0
	v_mov_b64_e32 v[96:97], 0
	v_mov_b64_e32 v[102:103], 0
	v_mov_b64_e32 v[104:105], 0
	v_mov_b64_e32 v[110:111], 0
	v_mov_b64_e32 v[112:113], 0
	v_mov_b64_e32 v[114:115], 0
	v_mov_b64_e32 v[116:117], 0
	v_mov_b64_e32 v[118:119], 0
	v_mov_b64_e32 v[120:121], 0
	v_mov_b64_e32 v[122:123], 0
	v_mov_b64_e32 v[124:125], 0
	v_mov_b64_e32 v[126:127], 0
	v_mov_b64_e32 v[128:129], 0
	s_setprio 1
	s_cmp_eq_u64 s[10:11], 0
	s_cbranch_scc1 .Lsp_LBB0_839
	s_setprio 0

; template <class Epi, class Sched, bool ALIGN_EPI = false, bool SP2 = false>
; __device__ __forceinline__ void gemm_phase(PG8_LAS unsigned char* lds, const Gemm g, const Sched& S, const Epi& E) {
;     ...
;         const char* nA = has_next ? (const char*)g.A + (size_t)nxt.pm * tstepA + (size_t)((nxt.pn >> g.a_shift) * g.a_stride) : cA; const char* nB = has_next ? (const char*)g.Bt + (size_t)nxt.pn * tstepB : cB;
; #pragma clang loop unroll(disable)
;         for (int t = 0; t < nt; t += 2) {
;             const bool last = (t == nt - 2);
;             const char* a1 = cA + (size_t)(t + 1) * kstep;
;             const char* a2 = last ? nA : cA + (size_t)(t + 2) * kstep; const char* b2 = last ? nB : cB + (size_t)(t + 2) * kstep;
;             const char* a3 = a2 + kstep; const char* b3 = b2 + kstep;
;     ...
; #pragma unroll
;         for (int a = 0; a < 2; ++a)
; #pragma unroll
;             for (int b = 0; b < 2; ++b)
; #pragma unroll
;                 for (int m = 0; m < 4; ++m)
; #pragma unroll
;                     for (int n = 0; n < 2; ++n) acc[a][b][m][n] = (f32x4){0.f, 0.f, 0.f, 0.f};
.LBB0_989:
	s_ashr_i32 s23, s22, 31
	s_lshl_b64 s[24:25], s[22:23], 21
	s_add_u32 s24, s92, s24
	s_addc_u32 s25, s93, s25
	s_and_b64 s[34:35], s[6:7], exec
	s_cselect_b32 s23, s25, s41
	s_cselect_b32 s27, s24, s40
	s_ashr_i32 s21, s20, 31
	s_lshl_b64 s[34:35], s[20:21], 21
	s_add_u32 s36, s54, s34
	s_addc_u32 s37, s55, s35
	s_and_b64 s[34:35], s[6:7], exec
	s_cselect_b32 s21, s37, s43
	s_cselect_b32 s39, s36, s42
	s_add_u32 s40, s40, 0x100080
	s_addc_u32 s41, s41, 0
	s_add_u32 s72, s42, 0x100
	v_mov_b32_e32 v2, 0
	s_addc_u32 s73, s43, 0
	s_mov_b32 s74, -2
	v_mov_b32_e32 v3, v2
	v_mov_b64_e32 v[4:5], 0
	v_mov_b64_e32 v[6:7], 0
	v_mov_b64_e32 v[8:9], 0
	v_mov_b64_e32 v[10:11], 0
	v_mov_b64_e32 v[12:13], 0
	v_mov_b64_e32 v[14:15], 0
	v_mov_b64_e32 v[16:17], 0
	v_mov_b64_e32 v[18:19], 0
	v_mov_b64_e32 v[20:21], 0
	v_mov_b64_e32 v[22:23], 0
	v_mov_b64_e32 v[24:25], 0
	v_mov_b64_e32 v[26:27], 0
	v_mov_b64_e32 v[28:29], 0
	v_mov_b64_e32 v[30:31], 0
	v_mov_b64_e32 v[32:33], 0
	v_mov_b64_e32 v[66:67], 0
	v_mov_b64_e32 v[68:69], 0
	v_mov_b64_e32 v[70:71], 0
	v_mov_b64_e32 v[72:73], 0
	v_mov_b64_e32 v[74:75], 0
	v_mov_b64_e32 v[76:77], 0
	v_mov_b64_e32 v[78:79], 0
	v_mov_b64_e32 v[80:81], 0
	v_mov_b64_e32 v[82:83], 0
	v_mov_b64_e32 v[84:85], 0
	v_mov_b64_e32 v[86:87], 0
	v_mov_b64_e32 v[88:89], 0
	v_mov_b64_e32 v[90:91], 0
	v_mov_b64_e32 v[92:93], 0
	v_mov_b64_e32 v[94:95], 0
	v_mov_b64_e32 v[96:97], 0
	v_mov_b64_e32 v[34:35], 0
	v_mov_b64_e32 v[36:37], 0
	v_mov_b64_e32 v[38:39], 0
	v_mov_b64_e32 v[40:41], 0
	v_mov_b64_e32 v[42:43], 0
	v_mov_b64_e32 v[44:45], 0
	v_mov_b64_e32 v[46:47], 0
	v_mov_b64_e32 v[48:49], 0
	v_mov_b64_e32 v[50:51], 0
	v_mov_b64_e32 v[52:53], 0
	v_mov_b64_e32 v[54:55], 0
	v_mov_b64_e32 v[56:57], 0
	v_mov_b64_e32 v[58:59], 0
	v_mov_b64_e32 v[60:61], 0
	v_mov_b64_e32 v[62:63], 0
	v_mov_b64_e32 v[64:65], 0
	v_mov_b64_e32 v[98:99], 0
	v_mov_b64_e32 v[100:101], 0
	v_mov_b64_e32 v[102:103], 0
	v_mov_b64_e32 v[104:105], 0
	v_mov_b64_e32 v[106:107], 0
	v_mov_b64_e32 v[108:109], 0
	v_mov_b64_e32 v[110:111], 0
	v_mov_b64_e32 v[112:113], 0
	v_mov_b64_e32 v[114:115], 0
	v_mov_b64_e32 v[116:117], 0
	v_mov_b64_e32 v[118:119], 0
	v_mov_b64_e32 v[120:121], 0
	v_mov_b64_e32 v[122:123], 0
	v_mov_b64_e32 v[124:125], 0
	v_mov_b64_e32 v[126:127], 0
	v_mov_b64_e32 v[128:129], 0
	s_setprio 1
	s_cmp_eq_u64 s[12:13], 0
	s_cbranch_scc1 .Lsp_LBB0_990
	s_setprio 0

; template <class Epi, class Sched, bool ALIGN_EPI = false, bool SP2 = false>
; __device__ __forceinline__ void gemm_phase(PG8_LAS unsigned char* lds, const Gemm g, const Sched& S, const Epi& E) {
;     ...
;         const char* nA = has_next ? (const char*)g.A + (size_t)nxt.pm * tstepA + (size_t)((nxt.pn >> g.a_shift) * g.a_stride) : cA; const char* nB = has_next ? (const char*)g.Bt + (size_t)nxt.pn * tstepB : cB;
; #pragma clang loop unroll(disable)
;         for (int t = 0; t < nt; t += 2) {
;             const bool last = (t == nt - 2);
;             const char* a1 = cA + (size_t)(t + 1) * kstep;
;             const char* a2 = last ? nA : cA + (size_t)(t + 2) * kstep; const char* b2 = last ? nB : cB + (size_t)(t + 2) * kstep;
;             const char* a3 = a2 + kstep; const char* b3 = b2 + kstep;
;     ...
; #pragma unroll
;         for (int a = 0; a < 2; ++a)
; #pragma unroll
;             for (int b = 0; b < 2; ++b)
; #pragma unroll
;                 for (int m = 0; m < 4; ++m)
; #pragma unroll
;                     for (int n = 0; n < 2; ++n) acc[a][b][m][n] = (f32x4){0.f, 0.f, 0.f, 0.f};
.LBB0_1126:
	s_ashr_i32 s25, s24, 31
	s_lshl_b64 s[26:27], s[24:25], 21
	s_add_u32 s36, s54, s26
	s_addc_u32 s37, s55, s27
	s_and_b64 s[26:27], s[4:5], exec
	s_cselect_b32 s25, s37, s41
	s_cselect_b32 s26, s36, s40
	s_ashr_i32 s23, s22, 31
	s_lshl_b64 s[34:35], s[22:23], 21
	s_add_u32 s38, s19, s34
	s_addc_u32 s39, s21, s35
	s_and_b64 s[34:35], s[4:5], exec
	s_cselect_b32 s23, s39, s43
	s_cselect_b32 s27, s38, s42
	s_add_u32 s40, s40, 0x100080
	s_addc_u32 s41, s41, 0
	s_add_u32 s45, s42, 0x100
	v_mov_b32_e32 v2, 0
	s_addc_u32 s52, s43, 0
	s_mov_b32 s53, -2
	v_mov_b32_e32 v3, v2
	v_mov_b64_e32 v[4:5], 0
	v_mov_b64_e32 v[14:15], 0
	v_mov_b64_e32 v[16:17], 0
	v_mov_b64_e32 v[18:19], 0
	v_mov_b64_e32 v[20:21], 0
	v_mov_b64_e32 v[30:31], 0
	v_mov_b64_e32 v[32:33], 0
	v_mov_b64_e32 v[34:35], 0
	v_mov_b64_e32 v[36:37], 0
	v_mov_b64_e32 v[46:47], 0
	v_mov_b64_e32 v[48:49], 0
	v_mov_b64_e32 v[50:51], 0
	v_mov_b64_e32 v[52:53], 0
	v_mov_b64_e32 v[62:63], 0
	v_mov_b64_e32 v[64:65], 0
	v_mov_b64_e32 v[6:7], 0
	v_mov_b64_e32 v[8:9], 0
	v_mov_b64_e32 v[10:11], 0
	v_mov_b64_e32 v[12:13], 0
	v_mov_b64_e32 v[22:23], 0
	v_mov_b64_e32 v[24:25], 0
	v_mov_b64_e32 v[26:27], 0
	v_mov_b64_e32 v[28:29], 0
	v_mov_b64_e32 v[38:39], 0
	v_mov_b64_e32 v[40:41], 0
	v_mov_b64_e32 v[42:43], 0
	v_mov_b64_e32 v[44:45], 0
	v_mov_b64_e32 v[54:55], 0
	v_mov_b64_e32 v[56:57], 0
	v_mov_b64_e32 v[58:59], 0
	v_mov_b64_e32 v[60:61], 0
	v_mov_b64_e32 v[66:67], 0
	v_mov_b64_e32 v[68:69], 0
	v_mov_b64_e32 v[78:79], 0
	v_mov_b64_e32 v[80:81], 0
	v_mov_b64_e32 v[82:83], 0
	v_mov_b64_e32 v[84:85], 0
	v_mov_b64_e32 v[94:95], 0
	v_mov_b64_e32 v[96:97], 0
	v_mov_b64_e32 v[98:99], 0
	v_mov_b64_e32 v[100:101], 0
	v_mov_b64_e32 v[110:111], 0
	v_mov_b64_e32 v[112:113], 0
	v_mov_b64_e32 v[114:115], 0
	v_mov_b64_e32 v[116:117], 0
	v_mov_b64_e32 v[126:127], 0
	v_mov_b64_e32 v[128:129], 0
	v_mov_b64_e32 v[70:71], 0
	v_mov_b64_e32 v[72:73], 0
	v_mov_b64_e32 v[74:75], 0
	v_mov_b64_e32 v[76:77], 0
	v_mov_b64_e32 v[86:87], 0
	v_mov_b64_e32 v[88:89], 0
	v_mov_b64_e32 v[90:91], 0
	v_mov_b64_e32 v[92:93], 0
	v_mov_b64_e32 v[102:103], 0
	v_mov_b64_e32 v[104:105], 0
	v_mov_b64_e32 v[106:107], 0
	v_mov_b64_e32 v[108:109], 0
	v_mov_b64_e32 v[118:119], 0
	v_mov_b64_e32 v[120:121], 0
	v_mov_b64_e32 v[122:123], 0
	v_mov_b64_e32 v[124:125], 0
	v_readfirstlane_b32 s98, v0
	s_nop 1
	s_cmpk_gt_u32 s98, 0x7f
	s_cbranch_scc1 .Lp11_st_skip
	s_lshl_b32 s98, s6, 11
	s_add_u32 s100, s8, s98
	s_addc_u32 s101, s9, 0
	v_lshlrev_b32_e32 v232, 4, v0
	global_load_dwordx4 v[228:231], v232, s[100:101]

; template <class Epi, class Sched, bool ALIGN_EPI = false, bool SP2 = false>
; __device__ __forceinline__ void gemm_phase(PG8_LAS unsigned char* lds, const Gemm g, const Sched& S, const Epi& E) {
;     ...
;         const char* nA = has_next ? (const char*)g.A + (size_t)nxt.pm * tstepA + (size_t)((nxt.pn >> g.a_shift) * g.a_stride) : cA; const char* nB = has_next ? (const char*)g.Bt + (size_t)nxt.pn * tstepB : cB;
; #pragma clang loop unroll(disable)
;         for (int t = 0; t < nt; t += 2) {
;             const bool last = (t == nt - 2);
;             const char* a1 = cA + (size_t)(t + 1) * kstep;
;             const char* a2 = last ? nA : cA + (size_t)(t + 2) * kstep; const char* b2 = last ? nB : cB + (size_t)(t + 2) * kstep;
;             const char* a3 = a2 + kstep; const char* b3 = b2 + kstep;
;     ...
; #pragma unroll
;         for (int a = 0; a < 2; ++a)
; #pragma unroll
;             for (int b = 0; b < 2; ++b)
; #pragma unroll
;                 for (int m = 0; m < 4; ++m)
; #pragma unroll
;                     for (int n = 0; n < 2; ++n) acc[a][b][m][n] = (f32x4){0.f, 0.f, 0.f, 0.f};
.LBB0_1205:
	s_add_u32 s62, s36, 0x100
	v_mov_b32_e32 v2, 0
	s_addc_u32 s63, s37, 0
	s_mov_b32 s64, -2
	v_mov_b32_e32 v3, v2
	v_mov_b64_e32 v[4:5], 0
	v_mov_b64_e32 v[6:7], 0
	v_mov_b64_e32 v[8:9], 0
	v_mov_b64_e32 v[14:15], 0
	v_mov_b64_e32 v[16:17], 0
	v_mov_b64_e32 v[22:23], 0
	v_mov_b64_e32 v[24:25], 0
	v_mov_b64_e32 v[30:31], 0
	v_mov_b64_e32 v[32:33], 0
	v_mov_b64_e32 v[38:39], 0
	v_mov_b64_e32 v[40:41], 0
	v_mov_b64_e32 v[46:47], 0
	v_mov_b64_e32 v[48:49], 0
	v_mov_b64_e32 v[54:55], 0
	v_mov_b64_e32 v[56:57], 0
	v_mov_b64_e32 v[10:11], 0
	v_mov_b64_e32 v[12:13], 0
	v_mov_b64_e32 v[18:19], 0
	v_mov_b64_e32 v[20:21], 0
	v_mov_b64_e32 v[26:27], 0
	v_mov_b64_e32 v[28:29], 0
	v_mov_b64_e32 v[34:35], 0
	v_mov_b64_e32 v[36:37], 0
	v_mov_b64_e32 v[42:43], 0
	v_mov_b64_e32 v[44:45], 0
	v_mov_b64_e32 v[50:51], 0
	v_mov_b64_e32 v[52:53], 0
	v_mov_b64_e32 v[58:59], 0
	v_mov_b64_e32 v[60:61], 0
	v_mov_b64_e32 v[62:63], 0
	v_mov_b64_e32 v[64:65], 0
	v_mov_b64_e32 v[66:67], 0
	v_mov_b64_e32 v[68:69], 0
	v_mov_b64_e32 v[70:71], 0
	v_mov_b64_e32 v[72:73], 0
	v_mov_b64_e32 v[74:75], 0
	v_mov_b64_e32 v[76:77], 0
	v_mov_b64_e32 v[78:79], 0
	v_mov_b64_e32 v[80:81], 0
	v_mov_b64_e32 v[82:83], 0
	v_mov_b64_e32 v[84:85], 0
	v_mov_b64_e32 v[90:91], 0
	v_mov_b64_e32 v[92:93], 0
	v_mov_b64_e32 v[98:99], 0
	v_mov_b64_e32 v[100:101], 0
	v_mov_b64_e32 v[106:107], 0
	v_mov_b64_e32 v[108:109], 0
	v_mov_b64_e32 v[86:87], 0
	v_mov_b64_e32 v[88:89], 0
	v_mov_b64_e32 v[94:95], 0
	v_mov_b64_e32 v[96:97], 0
	v_mov_b64_e32 v[102:103], 0
	v_mov_b64_e32 v[104:105], 0
	v_mov_b64_e32 v[110:111], 0
	v_mov_b64_e32 v[112:113], 0
	v_mov_b64_e32 v[114:115], 0
	v_mov_b64_e32 v[116:117], 0
	v_mov_b64_e32 v[118:119], 0
	v_mov_b64_e32 v[120:121], 0
	v_mov_b64_e32 v[122:123], 0
	v_mov_b64_e32 v[124:125], 0
	v_mov_b64_e32 v[126:127], 0
	v_mov_b64_e32 v[128:129], 0
	s_setprio 1
	s_cmp_eq_u64 s[12:13], 0
	s_cbranch_scc1 .Lsp_LBB0_1206
	s_setprio 0
